# prologue: the two gain-scaled weight-transpose variants issue their 8 gain + 8 row loads together and wait once (was 8 serial load/wait round trips per item); on top of the pipelined attention
# speedup vs baseline: 1.0087x; 1.0087x over previous
; #define LAS __attribute__((address_space(3)))
; #define LDS_WAIT() asm volatile("s_waitcnt lgkmcnt(0)" ::: "memory")
; __device__ __forceinline__ unsigned cvtpk(float lo, float hi) { f32x2_t v = {lo, hi}; bf16x2_t b = __builtin_convertvector(v, bf16x2_t); return __builtin_bit_cast(unsigned, b); }
; __device__ __forceinline__ int sigma_col(int n) { return (n & ~0x30) | ((n & 0x10) << 1) | ((n & 0x20) >> 1); }
; __device__ __forceinline__ void transpose_item(const float* W, int K, int N, bf16* WT, const float* g, bool perm, LAS float* scr, int item, int lane) {
;     ...
;     LDS_WAIT(); asm volatile("" ::: "memory");
;     const int c = lane & 7;
; #pragma unroll
;     for (int j = 0; j < 4; ++j) { const int n = (lane >> 3) + 8 * j; const LAS float* s = scr + (8 * c) * 33 + n;
;         u32x4 o; o.x = cvtpk(s[0 * 33], s[1 * 33]); o.y = cvtpk(s[2 * 33], s[3 * 33]); o.z = cvtpk(s[4 * 33], s[5 * 33]); o.w = cvtpk(s[6 * 33], s[7 * 33]);
;         const int dn = perm ? sigma_col(n0 + n) : (n0 + n);
;         *(u32x4*)(WT + (size_t)dn * K + k0 + 8 * c) = o; }
;     LDS_WAIT(); asm volatile("" ::: "memory");
.Lpro_B_tail:
	s_waitcnt lgkmcnt(0)
	ds_read2_b32 v[48:49], v31 offset0:33 offset1:41
	ds_read2_b32 v[50:51], v31 offset1:8
	ds_read2_b32 v[52:53], v31 offset0:66 offset1:74
	ds_read2_b32 v[54:55], v31 offset0:99 offset1:107
	ds_read2_b32 v[56:57], v31 offset0:132 offset1:140
	ds_read2_b32 v[58:59], v31 offset0:165 offset1:173
	ds_read2_b32 v[68:69], v31 offset0:198 offset1:206
	ds_read2_b32 v[70:71], v31 offset0:231 offset1:239
	ds_read2_b32 v[72:73], v31 offset0:49 offset1:57
	ds_read2_b32 v[74:75], v31 offset0:16 offset1:24
	ds_read2_b32 v[76:77], v31 offset0:82 offset1:90
	ds_read2_b32 v[78:79], v31 offset0:115 offset1:123
	ds_read2_b32 v[80:81], v31 offset0:148 offset1:156
	ds_read2_b32 v[82:83], v31 offset0:181 offset1:189
	ds_read2_b32 v[84:85], v31 offset0:214 offset1:222
	ds_read2_b32 v[86:87], v31 offset0:247 offset1:255
	s_waitcnt lgkmcnt(14)
	v_cvt_pk_bf16_f32 v20, v50, v48
	s_waitcnt lgkmcnt(12)
	v_cvt_pk_bf16_f32 v21, v52, v54
	s_waitcnt lgkmcnt(10)
	v_cvt_pk_bf16_f32 v22, v56, v58
	s_waitcnt lgkmcnt(8)
	v_cvt_pk_bf16_f32 v23, v68, v70
	v_cvt_pk_bf16_f32 v48, v51, v49
	v_cvt_pk_bf16_f32 v49, v53, v55
	v_cvt_pk_bf16_f32 v50, v57, v59
	v_cvt_pk_bf16_f32 v51, v69, v71
	s_waitcnt lgkmcnt(6)
	v_cvt_pk_bf16_f32 v52, v74, v72
	s_waitcnt lgkmcnt(4)
	v_cvt_pk_bf16_f32 v53, v76, v78
	s_waitcnt lgkmcnt(2)
	v_cvt_pk_bf16_f32 v54, v80, v82
	s_waitcnt lgkmcnt(0)
	v_cvt_pk_bf16_f32 v55, v84, v86
	v_cvt_pk_bf16_f32 v56, v75, v73
	v_cvt_pk_bf16_f32 v57, v77, v79
	v_cvt_pk_bf16_f32 v58, v81, v83
	v_cvt_pk_bf16_f32 v59, v85, v87
	global_store_dwordx4 v[60:61], v[20:23], off
	global_store_dwordx4 v[62:63], v[48:51], off
	global_store_dwordx4 v[64:65], v[52:55], off
	global_store_dwordx4 v[66:67], v[56:59], off
	s_waitcnt lgkmcnt(0)

; #define LAS __attribute__((address_space(3)))
; #define LDS_WAIT() asm volatile("s_waitcnt lgkmcnt(0)" ::: "memory")
; __device__ __forceinline__ unsigned cvtpk(float lo, float hi) { f32x2_t v = {lo, hi}; bf16x2_t b = __builtin_convertvector(v, bf16x2_t); return __builtin_bit_cast(unsigned, b); }
; __device__ __forceinline__ int sigma_col(int n) { return (n & ~0x30) | ((n & 0x10) << 1) | ((n & 0x20) >> 1); }
; __device__ __forceinline__ void transpose_item(const float* W, int K, int N, bf16* WT, const float* g, bool perm, LAS float* scr, int item, int lane) {
;     const int nblk = N / 32, kb = item / nblk, nb = item % nblk, k0 = 64 * kb, n0 = 32 * nb;
;     const int ksub = lane >> 3, n4 = (lane & 7) * 4;
; #pragma unroll
;     for (int i = 0; i < 8; ++i) {
;         const int kk = 8 * i + ksub; const float gv = g ? g[k0 + kk] : 1.0f;
;         const f32x4 v = *(const f32x4*)(W + (size_t)(k0 + kk) * N + n0 + n4);
;         LAS float* d = scr + kk * 33 + n4;
;         d[0] = v[0] * gv; d[1] = v[1] * gv; d[2] = v[2] * gv; d[3] = v[3] * gv;
;     }
;     LDS_WAIT(); asm volatile("" ::: "memory");
;     const int c = lane & 7;
; #pragma unroll
;     for (int j = 0; j < 4; ++j) { const int n = (lane >> 3) + 8 * j; const LAS float* s = scr + (8 * c) * 33 + n;
;         u32x4 o; o.x = cvtpk(s[0 * 33], s[1 * 33]); o.y = cvtpk(s[2 * 33], s[3 * 33]); o.z = cvtpk(s[4 * 33], s[5 * 33]); o.w = cvtpk(s[6 * 33], s[7 * 33]);
;         const int dn = perm ? sigma_col(n0 + n) : (n0 + n);
;         *(u32x4*)(WT + (size_t)dn * K + k0 + 8 * c) = o; }
;     LDS_WAIT(); asm volatile("" ::: "memory");
.LBB0_17:
	s_andn2_b64 vcc, exec, s[2:3]
	s_cbranch_vccnz .LBB0_37
	s_add_i32 s0, s19, 0xf800
	s_lshr_b32 s0, s0, 1
	s_and_b32 s11, s0, 0x7fc0
	v_cndmask_b32_e64 v20, 0, 1, s[4:5]
	s_and_b32 s10, s14, 0xfe0
	v_add_lshl_u32 v23, s11, v140, 2
	v_cmp_ne_u32_e64 s[2:3], 1, v20
	global_load_dword v76, v23, s[70:71]
	global_load_dword v77, v23, s[70:71] offset:32
	global_load_dword v78, v23, s[70:71] offset:64
	global_load_dword v79, v23, s[70:71] offset:96
	global_load_dword v80, v23, s[70:71] offset:128
	global_load_dword v81, v23, s[70:71] offset:160
	global_load_dword v82, v23, s[70:71] offset:192
	global_load_dword v83, v23, s[70:71] offset:224
	s_lshl_b32 s0, s10, 2
	v_lshl_add_u64 v[20:21], v[14:15], 0, s[0:1]
	v_or_b32_e32 v2, s11, v140
	v_lshlrev_b32_e32 v2, 14, v2
	v_lshl_add_u64 v[48:49], v[20:21], 0, v[2:3]
	v_or_b32_e32 v2, s11, v1
	v_lshlrev_b32_e32 v2, 14, v2
	v_lshl_add_u64 v[52:53], v[20:21], 0, v[2:3]
	v_or_b32_e32 v2, s11, v25
	v_lshlrev_b32_e32 v2, 14, v2
	v_lshl_add_u64 v[56:57], v[20:21], 0, v[2:3]
	v_or_b32_e32 v2, s11, v26
	v_lshlrev_b32_e32 v2, 14, v2
	v_lshl_add_u64 v[60:61], v[20:21], 0, v[2:3]
	v_or_b32_e32 v2, s11, v27
	v_lshlrev_b32_e32 v2, 14, v2
	v_lshl_add_u64 v[64:65], v[20:21], 0, v[2:3]
	v_or_b32_e32 v2, s11, v28
	v_lshlrev_b32_e32 v2, 14, v2
	v_lshl_add_u64 v[68:69], v[20:21], 0, v[2:3]
	v_or_b32_e32 v2, s11, v29
	v_lshlrev_b32_e32 v2, 14, v2
	v_lshl_add_u64 v[72:73], v[20:21], 0, v[2:3]
	v_or_b32_e32 v2, s11, v30
	v_lshlrev_b32_e32 v2, 14, v2
	v_lshl_add_u64 v[84:85], v[20:21], 0, v[2:3]
	global_load_dwordx4 v[48:51], v[48:49], off
	s_nop 0
	global_load_dwordx4 v[52:55], v[52:53], off
	s_nop 0
	global_load_dwordx4 v[56:59], v[56:57], off
	s_nop 0
	global_load_dwordx4 v[60:63], v[60:61], off
	s_nop 0
	global_load_dwordx4 v[64:67], v[64:65], off
	s_nop 0
	global_load_dwordx4 v[68:71], v[68:69], off
	s_nop 0
	global_load_dwordx4 v[72:75], v[72:73], off
	s_nop 0
	global_load_dwordx4 v[84:87], v[84:85], off
	s_nop 0
	s_waitcnt vmcnt(7)
	v_mul_f32_e32 v48, v76, v48
	v_mul_f32_e32 v49, v76, v49
	v_mul_f32_e32 v50, v76, v50
	v_mul_f32_e32 v51, v76, v51
	ds_write2_b32 v32, v48, v49 offset1:1
	ds_write2_b32 v32, v50, v51 offset0:2 offset1:3
	s_waitcnt vmcnt(6)
	v_mul_f32_e32 v52, v77, v52
	v_mul_f32_e32 v53, v77, v53
	v_mul_f32_e32 v54, v77, v54
	v_mul_f32_e32 v55, v77, v55
	ds_write2_b32 v33, v52, v53 offset1:1
	ds_write2_b32 v34, v54, v55 offset1:1
	s_waitcnt vmcnt(5)
	v_mul_f32_e32 v56, v78, v56
	v_mul_f32_e32 v57, v78, v57
	v_mul_f32_e32 v58, v78, v58
	v_mul_f32_e32 v59, v78, v59
	ds_write2_b32 v35, v56, v57 offset1:1
	ds_write2_b32 v36, v58, v59 offset1:1
	s_waitcnt vmcnt(4)
	v_mul_f32_e32 v60, v79, v60
	v_mul_f32_e32 v61, v79, v61
	v_mul_f32_e32 v62, v79, v62
	v_mul_f32_e32 v63, v79, v63
	ds_write2_b32 v37, v60, v61 offset1:1
	ds_write2_b32 v38, v62, v63 offset1:1
	s_waitcnt vmcnt(3)
	v_mul_f32_e32 v64, v80, v64
	v_mul_f32_e32 v65, v80, v65
	v_mul_f32_e32 v66, v80, v66
	v_mul_f32_e32 v67, v80, v67
	ds_write2_b32 v39, v64, v65 offset1:1
	ds_write2_b32 v40, v66, v67 offset1:1
	s_waitcnt vmcnt(2)
	v_mul_f32_e32 v68, v81, v68
	v_mul_f32_e32 v69, v81, v69
	v_mul_f32_e32 v70, v81, v70
	v_mul_f32_e32 v71, v81, v71
	ds_write2_b32 v41, v68, v69 offset1:1
	ds_write2_b32 v42, v70, v71 offset1:1
	s_waitcnt vmcnt(1)
	v_mul_f32_e32 v72, v82, v72
	v_mul_f32_e32 v73, v82, v73
	v_mul_f32_e32 v74, v82, v74
	v_mul_f32_e32 v75, v82, v75
	ds_write2_b32 v43, v72, v73 offset1:1
	ds_write2_b32 v44, v74, v75 offset1:1
	s_waitcnt vmcnt(0)
	v_mul_f32_e32 v84, v83, v84
	v_mul_f32_e32 v85, v83, v85
	v_mul_f32_e32 v86, v83, v86
	v_mul_f32_e32 v87, v83, v87
	ds_write2_b32 v45, v84, v85 offset1:1
	ds_write2_b32 v46, v86, v87 offset1:1
	s_lshl_b32 s0, s11, 1
	v_or_b32_e32 v2, s10, v140
	v_or_b32_e32 v23, s10, v1
	v_lshl_add_u64 v[20:21], v[6:7], 0, s[0:1]
	v_lshlrev_b32_e32 v2, 11, v2
	v_or_b32_e32 v24, s10, v25
	v_lshl_add_u64 v[60:61], v[20:21], 0, v[2:3]
	v_lshlrev_b32_e32 v2, 11, v23
	v_or_b32_e32 v47, s10, v26
	v_lshl_add_u64 v[62:63], v[20:21], 0, v[2:3]
	v_lshlrev_b32_e32 v2, 11, v24
	v_lshl_add_u64 v[64:65], v[20:21], 0, v[2:3]
	v_lshlrev_b32_e32 v2, 11, v47
	v_lshl_add_u64 v[66:67], v[20:21], 0, v[2:3]
	s_waitcnt lgkmcnt(0)
	ds_read2_b32 v[48:49], v31 offset0:33 offset1:41
	ds_read2_b32 v[50:51], v31 offset1:8
	ds_read2_b32 v[52:53], v31 offset0:66 offset1:74
	ds_read2_b32 v[54:55], v31 offset0:99 offset1:107
	ds_read2_b32 v[56:57], v31 offset0:132 offset1:140
	ds_read2_b32 v[58:59], v31 offset0:165 offset1:173
	ds_read2_b32 v[68:69], v31 offset0:198 offset1:206
	ds_read2_b32 v[70:71], v31 offset0:231 offset1:239
	ds_read2_b32 v[72:73], v31 offset0:49 offset1:57
	ds_read2_b32 v[74:75], v31 offset0:16 offset1:24
	ds_read2_b32 v[76:77], v31 offset0:82 offset1:90
	ds_read2_b32 v[78:79], v31 offset0:115 offset1:123
	ds_read2_b32 v[80:81], v31 offset0:148 offset1:156
	ds_read2_b32 v[82:83], v31 offset0:181 offset1:189
	ds_read2_b32 v[84:85], v31 offset0:214 offset1:222
	ds_read2_b32 v[86:87], v31 offset0:247 offset1:255
	s_waitcnt lgkmcnt(14)
	v_cvt_pk_bf16_f32 v20, v50, v48
	s_waitcnt lgkmcnt(12)
	v_cvt_pk_bf16_f32 v21, v52, v54
	s_waitcnt lgkmcnt(10)
	v_cvt_pk_bf16_f32 v22, v56, v58
	s_waitcnt lgkmcnt(8)
	v_cvt_pk_bf16_f32 v23, v68, v70
	v_cvt_pk_bf16_f32 v48, v51, v49
	v_cvt_pk_bf16_f32 v49, v53, v55
	v_cvt_pk_bf16_f32 v50, v57, v59
	v_cvt_pk_bf16_f32 v51, v69, v71
	s_waitcnt lgkmcnt(6)
	v_cvt_pk_bf16_f32 v52, v74, v72
	s_waitcnt lgkmcnt(4)
	v_cvt_pk_bf16_f32 v53, v76, v78
	s_waitcnt lgkmcnt(2)
	v_cvt_pk_bf16_f32 v54, v80, v82
	s_waitcnt lgkmcnt(0)
	v_cvt_pk_bf16_f32 v55, v84, v86
	v_cvt_pk_bf16_f32 v56, v75, v73
	v_cvt_pk_bf16_f32 v57, v77, v79
	v_cvt_pk_bf16_f32 v58, v81, v83
	v_cvt_pk_bf16_f32 v59, v85, v87
	global_store_dwordx4 v[60:61], v[20:23], off
	global_store_dwordx4 v[62:63], v[48:51], off
	global_store_dwordx4 v[64:65], v[52:55], off
	global_store_dwordx4 v[66:67], v[56:59], off
	s_waitcnt lgkmcnt(0)

; #define LAS __attribute__((address_space(3)))
; #define LDS_WAIT() asm volatile("s_waitcnt lgkmcnt(0)" ::: "memory")
; __device__ __forceinline__ unsigned cvtpk(float lo, float hi) { f32x2_t v = {lo, hi}; bf16x2_t b = __builtin_convertvector(v, bf16x2_t); return __builtin_bit_cast(unsigned, b); }
; __device__ __forceinline__ int sigma_col(int n) { return (n & ~0x30) | ((n & 0x10) << 1) | ((n & 0x20) >> 1); }
; __device__ __forceinline__ void transpose_item(const float* W, int K, int N, bf16* WT, const float* g, bool perm, LAS float* scr, int item, int lane) {
;     const int nblk = N / 32, kb = item / nblk, nb = item % nblk, k0 = 64 * kb, n0 = 32 * nb;
;     const int ksub = lane >> 3, n4 = (lane & 7) * 4;
; #pragma unroll
;     for (int i = 0; i < 8; ++i) {
;         const int kk = 8 * i + ksub; const float gv = g ? g[k0 + kk] : 1.0f;
;         const f32x4 v = *(const f32x4*)(W + (size_t)(k0 + kk) * N + n0 + n4);
;         LAS float* d = scr + kk * 33 + n4;
;         d[0] = v[0] * gv; d[1] = v[1] * gv; d[2] = v[2] * gv; d[3] = v[3] * gv;
;     }
;     LDS_WAIT(); asm volatile("" ::: "memory");
;     const int c = lane & 7;
; #pragma unroll
;     for (int j = 0; j < 4; ++j) { const int n = (lane >> 3) + 8 * j; const LAS float* s = scr + (8 * c) * 33 + n;
;         u32x4 o; o.x = cvtpk(s[0 * 33], s[1 * 33]); o.y = cvtpk(s[2 * 33], s[3 * 33]); o.z = cvtpk(s[4 * 33], s[5 * 33]); o.w = cvtpk(s[6 * 33], s[7 * 33]);
;         const int dn = perm ? sigma_col(n0 + n) : (n0 + n);
;         *(u32x4*)(WT + (size_t)dn * K + k0 + 8 * c) = o; }
;     LDS_WAIT(); asm volatile("" ::: "memory");
.LBB0_41:
	s_andn2_b64 vcc, exec, s[2:3]
	s_cbranch_vccnz .LBB0_12
	s_mul_hi_i32 s0, s19, 0x2aaaaaab
	s_lshr_b32 s2, s0, 31
	s_ashr_i32 s0, s0, 4
	s_add_i32 s0, s0, s2
	s_lshl_b32 s12, s0, 6
	v_cndmask_b32_e64 v20, 0, 1, s[8:9]
	s_ashr_i32 s13, s12, 31
	v_readlane_b32 s36, v250, 10
	v_readlane_b32 s37, v250, 11
	v_readlane_b32 s38, v250, 12
	v_readlane_b32 s39, v250, 13
	v_readlane_b32 s40, v250, 14
	v_readlane_b32 s41, v250, 15
	v_readlane_b32 s42, v250, 16
	v_readlane_b32 s43, v250, 17
	v_readlane_b32 s44, v250, 18
	v_readlane_b32 s45, v250, 19
	v_readlane_b32 s46, v250, 20
	v_readlane_b32 s47, v250, 21
	v_readlane_b32 s48, v250, 22
	v_readlane_b32 s49, v250, 23
	v_readlane_b32 s50, v250, 24
	v_readlane_b32 s51, v250, 25
	v_lshl_add_u64 v[22:23], s[12:13], 0, v[140:141]
	s_nop 1
	v_lshl_add_u64 v[22:23], v[22:23], 2, s[50:51]
	global_load_dword v76, v[22:23], off
	global_load_dword v77, v[22:23], off offset:32
	global_load_dword v78, v[22:23], off offset:64
	global_load_dword v79, v[22:23], off offset:96
	global_load_dword v80, v[22:23], off offset:128
	global_load_dword v81, v[22:23], off offset:160
	global_load_dword v82, v[22:23], off offset:192
	global_load_dword v83, v[22:23], off offset:224
	s_mulk_i32 s0, 0xf400
	s_add_i32 s10, s14, s0
	s_ashr_i32 s11, s10, 31
	v_lshl_add_u64 v[20:21], s[10:11], 2, v[18:19]
	v_or_b32_e32 v22, s12, v140
	v_mad_i64_i32 v[48:49], s[2:3], v22, s18, v[20:21]
	v_or_b32_e32 v22, s12, v1
	v_mad_i64_i32 v[52:53], s[2:3], v22, s18, v[20:21]
	v_or_b32_e32 v22, s12, v25
	v_mad_i64_i32 v[56:57], s[2:3], v22, s18, v[20:21]
	v_or_b32_e32 v22, s12, v26
	v_mad_i64_i32 v[60:61], s[2:3], v22, s18, v[20:21]
	v_or_b32_e32 v22, s12, v27
	v_mad_i64_i32 v[64:65], s[2:3], v22, s18, v[20:21]
	v_or_b32_e32 v22, s12, v28
	v_mad_i64_i32 v[68:69], s[2:3], v22, s18, v[20:21]
	v_or_b32_e32 v22, s12, v29
	v_mad_i64_i32 v[72:73], s[2:3], v22, s18, v[20:21]
	v_or_b32_e32 v22, s12, v30
	v_mad_i64_i32 v[84:85], s[2:3], v22, s18, v[20:21]
	global_load_dwordx4 v[48:51], v[48:49], off
	s_nop 0
	global_load_dwordx4 v[52:55], v[52:53], off
	s_nop 0
	global_load_dwordx4 v[56:59], v[56:57], off
	s_nop 0
	global_load_dwordx4 v[60:63], v[60:61], off
	s_nop 0
	global_load_dwordx4 v[64:67], v[64:65], off
	s_nop 0
	global_load_dwordx4 v[68:71], v[68:69], off
	s_nop 0
	global_load_dwordx4 v[72:75], v[72:73], off
	s_nop 0
	global_load_dwordx4 v[84:87], v[84:85], off
	s_nop 0
	s_waitcnt vmcnt(7)
	v_mul_f32_e32 v48, v76, v48
	v_mul_f32_e32 v49, v76, v49
	v_mul_f32_e32 v50, v76, v50
	v_mul_f32_e32 v51, v76, v51
	ds_write2_b32 v32, v48, v49 offset1:1
	ds_write2_b32 v32, v50, v51 offset0:2 offset1:3
	s_waitcnt vmcnt(6)
	v_mul_f32_e32 v52, v77, v52
	v_mul_f32_e32 v53, v77, v53
	v_mul_f32_e32 v54, v77, v54
	v_mul_f32_e32 v55, v77, v55
	ds_write2_b32 v33, v52, v53 offset1:1
	ds_write2_b32 v34, v54, v55 offset1:1
	s_waitcnt vmcnt(5)
	v_mul_f32_e32 v56, v78, v56
	v_mul_f32_e32 v57, v78, v57
	v_mul_f32_e32 v58, v78, v58
	v_mul_f32_e32 v59, v78, v59
	ds_write2_b32 v35, v56, v57 offset1:1
	ds_write2_b32 v36, v58, v59 offset1:1
	s_waitcnt vmcnt(4)
	v_mul_f32_e32 v60, v79, v60
	v_mul_f32_e32 v61, v79, v61
	v_mul_f32_e32 v62, v79, v62
	v_mul_f32_e32 v63, v79, v63
	ds_write2_b32 v37, v60, v61 offset1:1
	ds_write2_b32 v38, v62, v63 offset1:1
	s_waitcnt vmcnt(3)
	v_mul_f32_e32 v64, v80, v64
	v_mul_f32_e32 v65, v80, v65
	v_mul_f32_e32 v66, v80, v66
	v_mul_f32_e32 v67, v80, v67
	ds_write2_b32 v39, v64, v65 offset1:1
	ds_write2_b32 v40, v66, v67 offset1:1
	s_waitcnt vmcnt(2)
	v_mul_f32_e32 v68, v81, v68
	v_mul_f32_e32 v69, v81, v69
	v_mul_f32_e32 v70, v81, v70
	v_mul_f32_e32 v71, v81, v71
	ds_write2_b32 v41, v68, v69 offset1:1
	ds_write2_b32 v42, v70, v71 offset1:1
	s_waitcnt vmcnt(1)
	v_mul_f32_e32 v72, v82, v72
	v_mul_f32_e32 v73, v82, v73
	v_mul_f32_e32 v74, v82, v74
	v_mul_f32_e32 v75, v82, v75
	ds_write2_b32 v43, v72, v73 offset1:1
	ds_write2_b32 v44, v74, v75 offset1:1
	s_waitcnt vmcnt(0)
	v_mul_f32_e32 v84, v83, v84
	v_mul_f32_e32 v85, v83, v85
	v_mul_f32_e32 v86, v83, v86
	v_mul_f32_e32 v87, v83, v87
	ds_write2_b32 v45, v84, v85 offset1:1
	ds_write2_b32 v46, v86, v87 offset1:1
	s_lshr_b32 s0, s10, 1
	s_lshr_b32 s3, s14, 1
	v_add_u32_e32 v24, s10, v140
	s_and_b32 s2, s10, 0xffffffc0
	s_and_b32 s0, s0, 16
	s_and_b32 s3, s3, 16
	v_add_u32_e32 v47, 24, v24
	s_or_b32 s2, s0, s2
	v_add_u32_e32 v24, s3, v24
	v_and_b32_e32 v47, 0xffffffcf, v47
	v_or_b32_e32 v50, s2, v140
	v_or_b32_e32 v52, s2, v1
	v_or_b32_e32 v54, 32, v24
	v_or3_b32 v56, s0, v47, 32
	v_ashrrev_i32_e32 v51, 31, v50
	v_ashrrev_i32_e32 v53, 31, v52
	v_ashrrev_i32_e32 v55, 31, v54
	v_ashrrev_i32_e32 v57, 31, v56
	v_lshl_add_u64 v[48:49], s[12:13], 1, v[10:11]
	v_lshlrev_b64 v[50:51], 11, v[50:51]
	v_lshlrev_b64 v[52:53], 11, v[52:53]
	v_lshlrev_b64 v[54:55], 11, v[54:55]
	v_lshlrev_b64 v[56:57], 11, v[56:57]
	v_lshl_add_u64 v[60:61], v[48:49], 0, v[50:51]
	v_lshl_add_u64 v[62:63], v[48:49], 0, v[52:53]
	v_lshl_add_u64 v[64:65], v[48:49], 0, v[54:55]
	v_lshl_add_u64 v[66:67], v[48:49], 0, v[56:57]
	s_branch .Lpro_B_tail
